# EpiIn (P1) row statistics rewritten: batched SSQ loads, rsq+Newton rstd
# speedup vs baseline: 1.0107x; 1.0107x over previous
; __device__ __forceinline__ void load_rstd8(const float* ssq, const float* ssqc, int row0, int fq, float (&rs)[2][4]) {
;     const bool isc = row0 >= ML;
; #pragma unroll
;     for (int ai = 0; ai < 2; ++ai)
; #pragma unroll
;         for (int m = 0; m < 4; ++m) {
;             const int row = row0 + ai * HALF + m * 16;
;             float s;
;             if (!isc) { const f32x4 a = *(const f32x4*)(ssq + ((size_t)(2 * fq) * MT + row) * 4), b = *(const f32x4*)(ssq + ((size_t)(2 * fq + 1) * MT + row) * 4);
;                 s = ((a[0] + a[1]) + (a[2] + a[3])) + ((b[0] + b[1]) + (b[2] + b[3])); }
;             else { s = 0.f;
; #pragma unroll
;                 for (int j = 0; j < 8; ++j) s += ssqc[(size_t)(fq * 8 + j) * MC + (row - ML)]; }
;             s += __shfl_xor(s, 16); s += __shfl_xor(s, 32);
;             rs[ai][m] = 1.0f / sqrtf(s * (1.0f / D) + EPS);
;         }
; }
.LBB0_272:
	s_lshl_b32 s40, s88, 8
	s_add_u32 s40, s40, s71
	v_add_u32_e32 v240, s40, v189
	v_xor_b32_e32 v243, 16, v201
	v_lshlrev_b32_e32 v243, 2, v243
	v_xor_b32_e32 v244, 32, v201
	v_lshlrev_b32_e32 v244, 2, v244
	s_cmp_ge_u32 s88, 32
	s_cbranch_scc1 .Lepiin_ctx_p1
	v_mul_u32_u24_e32 v228, 0x4400, v191
	v_add_u32_e32 v228, v228, v240
	v_lshlrev_b32_e32 v241, 4, v228
	v_add_u32_e32 v242, 0x22000, v241
	global_load_dwordx4 v[130:133], v241, s[46:47]
	global_load_dwordx4 v[134:137], v242, s[46:47]
	global_load_dwordx4 v[138:141], v241, s[46:47] offset:256
	global_load_dwordx4 v[142:145], v242, s[46:47] offset:256
	global_load_dwordx4 v[146:149], v241, s[46:47] offset:512
	global_load_dwordx4 v[150:153], v242, s[46:47] offset:512
	global_load_dwordx4 v[168:171], v241, s[46:47] offset:768
	global_load_dwordx4 v[172:175], v242, s[46:47] offset:768
	global_load_dwordx4 v[176:179], v241, s[46:47] offset:2048
	global_load_dwordx4 v[180:183], v242, s[46:47] offset:2048
	global_load_dwordx4 v[184:187], v241, s[46:47] offset:2304
	global_load_dwordx4 v[204:207], v242, s[46:47] offset:2304
	global_load_dwordx4 v[208:211], v241, s[46:47] offset:2560
	global_load_dwordx4 v[212:215], v242, s[46:47] offset:2560
	global_load_dwordx4 v[216:219], v241, s[46:47] offset:2816
	global_load_dwordx4 v[220:223], v242, s[46:47] offset:2816
	s_waitcnt vmcnt(15)
	v_add_f32_e32 v130, v130, v131
	v_add_f32_e32 v132, v132, v133
	s_waitcnt vmcnt(14)
	v_add_f32_e32 v134, v134, v135
	v_add_f32_e32 v136, v136, v137
	v_add_f32_e32 v130, v130, v132
	v_add_f32_e32 v134, v134, v136
	v_add_f32_e32 v130, v130, v134
	s_waitcnt vmcnt(13)
	v_add_f32_e32 v138, v138, v139
	v_add_f32_e32 v140, v140, v141
	s_waitcnt vmcnt(12)
	v_add_f32_e32 v142, v142, v143
	v_add_f32_e32 v144, v144, v145
	v_add_f32_e32 v138, v138, v140
	v_add_f32_e32 v142, v142, v144
	v_add_f32_e32 v138, v138, v142
	s_waitcnt vmcnt(11)
	v_add_f32_e32 v146, v146, v147
	v_add_f32_e32 v148, v148, v149
	s_waitcnt vmcnt(10)
	v_add_f32_e32 v150, v150, v151
	v_add_f32_e32 v152, v152, v153
	v_add_f32_e32 v146, v146, v148
	v_add_f32_e32 v150, v150, v152
	v_add_f32_e32 v146, v146, v150
	s_waitcnt vmcnt(9)
	v_add_f32_e32 v168, v168, v169
	v_add_f32_e32 v170, v170, v171
	s_waitcnt vmcnt(8)
	v_add_f32_e32 v172, v172, v173
	v_add_f32_e32 v174, v174, v175
	v_add_f32_e32 v168, v168, v170
	v_add_f32_e32 v172, v172, v174
	v_add_f32_e32 v168, v168, v172
	s_waitcnt vmcnt(7)
	v_add_f32_e32 v176, v176, v177
	v_add_f32_e32 v178, v178, v179
	s_waitcnt vmcnt(6)
	v_add_f32_e32 v180, v180, v181
	v_add_f32_e32 v182, v182, v183
	v_add_f32_e32 v176, v176, v178
	v_add_f32_e32 v180, v180, v182
	v_add_f32_e32 v176, v176, v180
	s_waitcnt vmcnt(5)
	v_add_f32_e32 v184, v184, v185
	v_add_f32_e32 v186, v186, v187
	s_waitcnt vmcnt(4)
	v_add_f32_e32 v204, v204, v205
	v_add_f32_e32 v206, v206, v207
	v_add_f32_e32 v184, v184, v186
	v_add_f32_e32 v204, v204, v206
	v_add_f32_e32 v184, v184, v204
	s_waitcnt vmcnt(3)
	v_add_f32_e32 v208, v208, v209
	v_add_f32_e32 v210, v210, v211
	s_waitcnt vmcnt(2)
	v_add_f32_e32 v212, v212, v213
	v_add_f32_e32 v214, v214, v215
	v_add_f32_e32 v208, v208, v210
	v_add_f32_e32 v212, v212, v214
	v_add_f32_e32 v208, v208, v212
	s_waitcnt vmcnt(1)
	v_add_f32_e32 v216, v216, v217
	v_add_f32_e32 v218, v218, v219
	s_waitcnt vmcnt(0)
	v_add_f32_e32 v220, v220, v221
	v_add_f32_e32 v222, v222, v223
	v_add_f32_e32 v216, v216, v218
	v_add_f32_e32 v220, v220, v222
	v_add_f32_e32 v216, v216, v220
	s_branch .Lepiin_join_p1
.Lepiin_ctx_p1:
	v_mul_u32_u24_e32 v228, 0x1000, v191
	v_add_u32_e32 v228, v228, v240
	v_add_u32_e32 v228, 0xffffe000, v228
	v_lshlrev_b32_e32 v241, 2, v228
	v_add_u32_e32 v242, 0x1000, v241
	v_add_u32_e32 v245, 0x2000, v241
	v_add_u32_e32 v246, 0x3000, v241
	global_load_dword v130, v241, s[48:49]
	global_load_dword v131, v241, s[48:49] offset:2048
	global_load_dword v132, v242, s[48:49]
	global_load_dword v133, v242, s[48:49] offset:2048
	global_load_dword v134, v245, s[48:49]
	global_load_dword v135, v245, s[48:49] offset:2048
	global_load_dword v136, v246, s[48:49]
	global_load_dword v137, v246, s[48:49] offset:2048
	global_load_dword v138, v241, s[48:49] offset:64
	global_load_dword v139, v241, s[48:49] offset:2112
	global_load_dword v140, v242, s[48:49] offset:64
	global_load_dword v141, v242, s[48:49] offset:2112
	global_load_dword v142, v245, s[48:49] offset:64
	global_load_dword v143, v245, s[48:49] offset:2112
	global_load_dword v144, v246, s[48:49] offset:64
	global_load_dword v145, v246, s[48:49] offset:2112
	global_load_dword v146, v241, s[48:49] offset:128
	global_load_dword v147, v241, s[48:49] offset:2176
	global_load_dword v148, v242, s[48:49] offset:128
	global_load_dword v149, v242, s[48:49] offset:2176
	global_load_dword v150, v245, s[48:49] offset:128
	global_load_dword v151, v245, s[48:49] offset:2176
	global_load_dword v152, v246, s[48:49] offset:128
	global_load_dword v153, v246, s[48:49] offset:2176
	global_load_dword v168, v241, s[48:49] offset:192
	global_load_dword v169, v241, s[48:49] offset:2240
	global_load_dword v170, v242, s[48:49] offset:192
	global_load_dword v171, v242, s[48:49] offset:2240
	global_load_dword v172, v245, s[48:49] offset:192
	global_load_dword v173, v245, s[48:49] offset:2240
	global_load_dword v174, v246, s[48:49] offset:192
	global_load_dword v175, v246, s[48:49] offset:2240
	global_load_dword v176, v241, s[48:49] offset:512
	global_load_dword v177, v241, s[48:49] offset:2560
	global_load_dword v178, v242, s[48:49] offset:512
	global_load_dword v179, v242, s[48:49] offset:2560
	global_load_dword v180, v245, s[48:49] offset:512
	global_load_dword v181, v245, s[48:49] offset:2560
	global_load_dword v182, v246, s[48:49] offset:512
	global_load_dword v183, v246, s[48:49] offset:2560
	global_load_dword v184, v241, s[48:49] offset:576
	global_load_dword v185, v241, s[48:49] offset:2624
	global_load_dword v186, v242, s[48:49] offset:576
	global_load_dword v187, v242, s[48:49] offset:2624
	global_load_dword v204, v245, s[48:49] offset:576
	global_load_dword v205, v245, s[48:49] offset:2624
	global_load_dword v206, v246, s[48:49] offset:576
	global_load_dword v207, v246, s[48:49] offset:2624
	global_load_dword v208, v241, s[48:49] offset:640
	global_load_dword v209, v241, s[48:49] offset:2688
	global_load_dword v210, v242, s[48:49] offset:640
	global_load_dword v211, v242, s[48:49] offset:2688
	global_load_dword v212, v245, s[48:49] offset:640
	global_load_dword v213, v245, s[48:49] offset:2688
	global_load_dword v214, v246, s[48:49] offset:640
	global_load_dword v215, v246, s[48:49] offset:2688
	global_load_dword v216, v241, s[48:49] offset:704
	global_load_dword v217, v241, s[48:49] offset:2752
	global_load_dword v218, v242, s[48:49] offset:704
	global_load_dword v219, v242, s[48:49] offset:2752
	global_load_dword v220, v245, s[48:49] offset:704
	global_load_dword v221, v245, s[48:49] offset:2752
	global_load_dword v222, v246, s[48:49] offset:704
	global_load_dword v223, v246, s[48:49] offset:2752
	s_waitcnt vmcnt(62)
; __device__ __forceinline__ void load_rstd8(const float* ssq, const float* ssqc, int row0, int fq, float (&rs)[2][4]) {
;     ...
;             else { s = 0.f;
; #pragma unroll
;                 for (int j = 0; j < 8; ++j) s += ssqc[(size_t)(fq * 8 + j) * MC + (row - ML)]; }
	v_add_f32_e32 v130, v130, v131
	s_waitcnt vmcnt(61)
	v_add_f32_e32 v130, v130, v132
	s_waitcnt vmcnt(60)
	v_add_f32_e32 v130, v130, v133
	s_waitcnt vmcnt(59)
	v_add_f32_e32 v130, v130, v134
	s_waitcnt vmcnt(58)
	v_add_f32_e32 v130, v130, v135
	s_waitcnt vmcnt(57)
	v_add_f32_e32 v130, v130, v136
	s_waitcnt vmcnt(56)
	v_add_f32_e32 v130, v130, v137
	s_waitcnt vmcnt(54)
	v_add_f32_e32 v138, v138, v139
	s_waitcnt vmcnt(53)
	v_add_f32_e32 v138, v138, v140
	s_waitcnt vmcnt(52)
	v_add_f32_e32 v138, v138, v141
	s_waitcnt vmcnt(51)
	v_add_f32_e32 v138, v138, v142
	s_waitcnt vmcnt(50)
	v_add_f32_e32 v138, v138, v143
	s_waitcnt vmcnt(49)
	v_add_f32_e32 v138, v138, v144
	s_waitcnt vmcnt(48)
	v_add_f32_e32 v138, v138, v145
	s_waitcnt vmcnt(46)
	v_add_f32_e32 v146, v146, v147
	s_waitcnt vmcnt(45)
	v_add_f32_e32 v146, v146, v148
	s_waitcnt vmcnt(44)
	v_add_f32_e32 v146, v146, v149
	s_waitcnt vmcnt(43)
	v_add_f32_e32 v146, v146, v150
	s_waitcnt vmcnt(42)
	v_add_f32_e32 v146, v146, v151
	s_waitcnt vmcnt(41)
	v_add_f32_e32 v146, v146, v152
	s_waitcnt vmcnt(40)
	v_add_f32_e32 v146, v146, v153
	s_waitcnt vmcnt(38)
	v_add_f32_e32 v168, v168, v169
	s_waitcnt vmcnt(37)
	v_add_f32_e32 v168, v168, v170
	s_waitcnt vmcnt(36)
	v_add_f32_e32 v168, v168, v171
	s_waitcnt vmcnt(35)
	v_add_f32_e32 v168, v168, v172
	s_waitcnt vmcnt(34)
	v_add_f32_e32 v168, v168, v173
	s_waitcnt vmcnt(33)
	v_add_f32_e32 v168, v168, v174
	s_waitcnt vmcnt(32)
	v_add_f32_e32 v168, v168, v175
	s_waitcnt vmcnt(30)
	v_add_f32_e32 v176, v176, v177
	s_waitcnt vmcnt(29)
	v_add_f32_e32 v176, v176, v178
	s_waitcnt vmcnt(28)
	v_add_f32_e32 v176, v176, v179
	s_waitcnt vmcnt(27)
	v_add_f32_e32 v176, v176, v180
	s_waitcnt vmcnt(26)
	v_add_f32_e32 v176, v176, v181
	s_waitcnt vmcnt(25)
	v_add_f32_e32 v176, v176, v182
	s_waitcnt vmcnt(24)
	v_add_f32_e32 v176, v176, v183
	s_waitcnt vmcnt(22)
	v_add_f32_e32 v184, v184, v185
	s_waitcnt vmcnt(21)
	v_add_f32_e32 v184, v184, v186
	s_waitcnt vmcnt(20)
	v_add_f32_e32 v184, v184, v187
	s_waitcnt vmcnt(19)
	v_add_f32_e32 v184, v184, v204
	s_waitcnt vmcnt(18)
	v_add_f32_e32 v184, v184, v205
	s_waitcnt vmcnt(17)
	v_add_f32_e32 v184, v184, v206
	s_waitcnt vmcnt(16)
	v_add_f32_e32 v184, v184, v207
	s_waitcnt vmcnt(14)
	v_add_f32_e32 v208, v208, v209
	s_waitcnt vmcnt(13)
	v_add_f32_e32 v208, v208, v210
	s_waitcnt vmcnt(12)
	v_add_f32_e32 v208, v208, v211
	s_waitcnt vmcnt(11)
	v_add_f32_e32 v208, v208, v212
	s_waitcnt vmcnt(10)
	v_add_f32_e32 v208, v208, v213
	s_waitcnt vmcnt(9)
	v_add_f32_e32 v208, v208, v214
	s_waitcnt vmcnt(8)
	v_add_f32_e32 v208, v208, v215
	s_waitcnt vmcnt(6)
	v_add_f32_e32 v216, v216, v217
	s_waitcnt vmcnt(5)
	v_add_f32_e32 v216, v216, v218
	s_waitcnt vmcnt(4)
	v_add_f32_e32 v216, v216, v219
	s_waitcnt vmcnt(3)
	v_add_f32_e32 v216, v216, v220
	s_waitcnt vmcnt(2)
	v_add_f32_e32 v216, v216, v221
	s_waitcnt vmcnt(1)
	v_add_f32_e32 v216, v216, v222
	s_waitcnt vmcnt(0)
	v_add_f32_e32 v216, v216, v223
; __device__ __forceinline__ void load_rstd8(const float* ssq, const float* ssqc, int row0, int fq, float (&rs)[2][4]) {
;     ...
;             s += __shfl_xor(s, 16); s += __shfl_xor(s, 32);
;             rs[ai][m] = 1.0f / sqrtf(s * (1.0f / D) + EPS);
;     __device__ __forceinline__ void operator()(const f32x4 (&acc)[2][2][4][2], const Unit& u, int wr, int wc, int fr_, int fq_) const {
;     ...
;         const int cpos = wc * 32 + 8 * fq;
;         const int colb = pn * BM + cpos;
;         f32x4 sh[2][2];
; #pragma unroll
;         for (int bj = 0; bj < 2; ++bj)
; #pragma unroll
;             for (int n = 0; n < 2; ++n) { const int dsrc = (wc < 2 ? 16 * wc + 4 * fq : 16 * wc + 4 * fq + 32) + 32 * n;
;                 sh[bj][n] = *(const f32x4*)(shw + (size_t)v * INW + (pn >= 12 && pn < 17 ? pn * BM + bj * HALF + dsrc : colb + bj * HALF + 4 * n)); }
.Lepiin_join_p1:
	s_waitcnt vmcnt(0)
	ds_bpermute_b32 v228, v243, v130
	ds_bpermute_b32 v229, v243, v138
	ds_bpermute_b32 v230, v243, v146
	ds_bpermute_b32 v231, v243, v168
	ds_bpermute_b32 v232, v243, v176
	ds_bpermute_b32 v233, v243, v184
	ds_bpermute_b32 v234, v243, v208
	ds_bpermute_b32 v235, v243, v216
	s_waitcnt lgkmcnt(7)
	v_add_f32_e32 v130, v130, v228
	s_waitcnt lgkmcnt(6)
	v_add_f32_e32 v138, v138, v229
	s_waitcnt lgkmcnt(5)
	v_add_f32_e32 v146, v146, v230
	s_waitcnt lgkmcnt(4)
	v_add_f32_e32 v168, v168, v231
	s_waitcnt lgkmcnt(3)
	v_add_f32_e32 v176, v176, v232
	s_waitcnt lgkmcnt(2)
	v_add_f32_e32 v184, v184, v233
	s_waitcnt lgkmcnt(1)
	v_add_f32_e32 v208, v208, v234
	s_waitcnt lgkmcnt(0)
	v_add_f32_e32 v216, v216, v235
	ds_bpermute_b32 v228, v244, v130
	ds_bpermute_b32 v229, v244, v138
	ds_bpermute_b32 v230, v244, v146
	ds_bpermute_b32 v231, v244, v168
	ds_bpermute_b32 v232, v244, v176
	ds_bpermute_b32 v233, v244, v184
	ds_bpermute_b32 v234, v244, v208
	ds_bpermute_b32 v235, v244, v216
	s_waitcnt lgkmcnt(7)
	v_add_f32_e32 v130, v130, v228
	s_waitcnt lgkmcnt(6)
	v_add_f32_e32 v138, v138, v229
	s_waitcnt lgkmcnt(5)
	v_add_f32_e32 v146, v146, v230
	s_waitcnt lgkmcnt(4)
	v_add_f32_e32 v168, v168, v231
	s_waitcnt lgkmcnt(3)
	v_add_f32_e32 v176, v176, v232
	s_waitcnt lgkmcnt(2)
	v_add_f32_e32 v184, v184, v233
	s_waitcnt lgkmcnt(1)
	v_add_f32_e32 v208, v208, v234
	s_waitcnt lgkmcnt(0)
	v_add_f32_e32 v216, v216, v235
	v_fmamk_f32 v130, v130, 0x3a000000, v195
	v_fmamk_f32 v138, v138, 0x3a000000, v195
	v_fmamk_f32 v146, v146, 0x3a000000, v195
	v_fmamk_f32 v168, v168, 0x3a000000, v195
	v_fmamk_f32 v176, v176, 0x3a000000, v195
	v_fmamk_f32 v184, v184, 0x3a000000, v195
	v_fmamk_f32 v208, v208, 0x3a000000, v195
	v_fmamk_f32 v216, v216, 0x3a000000, v195
	v_rsq_f32_e32 v134, v130
	v_rsq_f32_e32 v142, v138
	v_rsq_f32_e32 v150, v146
	v_rsq_f32_e32 v172, v168
	v_rsq_f32_e32 v180, v176
	v_rsq_f32_e32 v204, v184
	v_rsq_f32_e32 v212, v208
	v_rsq_f32_e32 v220, v216
	v_mul_f32_e32 v228, v130, v134
	v_mul_f32_e32 v229, v138, v142
	v_mul_f32_e32 v230, v146, v150
	v_mul_f32_e32 v231, v168, v172
	v_mul_f32_e32 v232, v176, v180
	v_mul_f32_e32 v233, v184, v204
	v_mul_f32_e32 v234, v208, v212
	v_mul_f32_e32 v235, v216, v220
	v_fma_f32 v228, -v228, v134, 1.0
	v_fma_f32 v229, -v229, v142, 1.0
	v_fma_f32 v230, -v230, v150, 1.0
	v_fma_f32 v231, -v231, v172, 1.0
	v_fma_f32 v232, -v232, v180, 1.0
	v_fma_f32 v233, -v233, v204, 1.0
	v_fma_f32 v234, -v234, v212, 1.0
	v_fma_f32 v235, -v235, v220, 1.0
	v_mul_f32_e32 v130, 0.5, v134
	v_mul_f32_e32 v138, 0.5, v142
	v_mul_f32_e32 v146, 0.5, v150
	v_mul_f32_e32 v168, 0.5, v172
	v_mul_f32_e32 v176, 0.5, v180
	v_mul_f32_e32 v184, 0.5, v204
	v_mul_f32_e32 v208, 0.5, v212
	v_mul_f32_e32 v216, 0.5, v220
	v_fma_f32 v200, v130, v228, v134
	v_fma_f32 v198, v138, v229, v142
	v_fma_f32 v196, v146, v230, v150
	v_fma_f32 v192, v168, v231, v172
	v_fma_f32 v190, v176, v232, v180
	v_fma_f32 v188, v184, v233, v204
	v_fma_f32 v0, v208, v234, v212
	v_fma_f32 v194, v216, v235, v220
	s_waitcnt lgkmcnt(0)
	v_mov_b32_e32 v240, v189
	v_mov_b32_e32 v150, v191
	s_lshl_b32 s26, s88, 8
	s_add_i32 s26, s26, s71
	v_add_u32_e32 v168, s26, v240
	v_ashrrev_i32_e32 v169, 31, v168
	v_lshlrev_b32_e32 v130, 3, v150
	v_add_u32_e32 v174, 16, v168
	v_ashrrev_i32_e32 v175, 31, v174
	v_add_u32_e32 v176, 32, v168
	v_ashrrev_i32_e32 v177, 31, v176
	v_add_u32_e32 v178, 48, v168
	v_ashrrev_i32_e32 v179, 31, v178
	v_add_u32_e32 v180, 0x80, v168
	v_ashrrev_i32_e32 v181, 31, v180
	v_add_u32_e32 v182, 0x90, v168
	v_ashrrev_i32_e32 v183, 31, v182
	v_add_u32_e32 v184, 0xa0, v168
	v_ashrrev_i32_e32 v185, 31, v184
	v_add_u32_e32 v186, 0xb0, v168
	v_ashrrev_i32_e32 v187, 31, v186
	s_lshl_b32 s26, s42, 8
	s_cmp_lt_u32 s88, 32
	v_add_u32_e32 v202, s77, v130
	v_lshlrev_b32_e32 v130, 2, v150
	v_add_u32_e32 v148, s95, v130
	v_add_u32_e32 v241, s26, v202
	v_add_u32_e32 v242, 0x80, v241
	s_movk_i32 s40, 0x1200
	s_cselect_b32 s40, s40, 0x2400
	s_cmp_gt_i32 s88, 15
	s_cselect_b32 s40, s40, 0
	s_lshl_b32 s40, s40, 2
	s_add_u32 s40, s68, s40
	s_addc_u32 s41, s69, 0
	s_add_i32 s43, s42, -12
	v_add_u32_e32 v131, s0, v130
	s_cmp_lt_u32 s43, 5
	v_cndmask_b32_e64 v130, v131, v148, s[36:37]
	s_cselect_b64 vcc, -1, 0
	v_add_u32_e32 v132, s26, v130
	v_cndmask_b32_e32 v130, v241, v132, vcc
	v_ashrrev_i32_e32 v131, 31, v130
	v_lshl_add_u64 v[130:131], v[130:131], 2, s[40:41]
	global_load_dwordx4 v[142:145], v[130:131], off
	v_add_u32_e32 v130, 32, v132
	v_or_b32_e32 v131, 4, v241
	v_cndmask_b32_e32 v130, v131, v130, vcc
	v_ashrrev_i32_e32 v131, 31, v130
	v_lshl_add_u64 v[130:131], v[130:131], 2, s[40:41]
	global_load_dwordx4 v[138:141], v[130:131], off
	v_add_u32_e32 v130, 0x80, v132
	v_cndmask_b32_e32 v130, v242, v130, vcc
	v_ashrrev_i32_e32 v131, 31, v130
	v_lshl_add_u64 v[130:131], v[130:131], 2, s[40:41]
	global_load_dwordx4 v[134:137], v[130:131], off
	v_add_u32_e32 v130, 0xa0, v132
	v_add_u32_e32 v131, 0x84, v241
	v_cndmask_b32_e32 v130, v131, v130, vcc
	v_ashrrev_i32_e32 v131, 31, v130
	v_lshl_add_u64 v[130:131], v[130:131], 2, s[40:41]
	global_load_dwordx4 v[130:133], v[130:131], off
	s_mov_b64 s[40:41], -1
	s_cmp_gt_i32 s42, 11
	s_cbranch_scc1 .LBB0_307
	s_andn2_b64 vcc, exec, s[40:41]
	s_cbranch_vccz .LBB0_328
